# v21 + k-slice-0 LDS-DMA issued right after the tile-top barrier in E2/M2/E4/O5/O2 prologues (ahead of epilogue-table loads)
# speedup vs baseline: 1.0165x; 1.0048x over previous
.LBB0_277:
	s_mul_hi_i32 s0, s18, 0x2aaaaaab
	s_lshr_b32 s1, s0, 31
	s_ashr_i32 s0, s0, 3
	s_add_i32 s0, s0, s1
	s_mul_i32 s1, s0, 48
	s_sub_i32 s1, s18, s1
	v_mov_b32_e32 v0, v155
	s_lshl_b32 s19, s1, 8
	s_lshl_b32 s0, s0, 8
	s_nop 0
	v_cmp_lt_i32_e32 vcc, s39, v0
	s_barrier
	v_lshrrev_b32_e32 v244, 4, v0
	v_xor_b32_e32 v244, v244, v0
	v_and_b32_e32 v244, 7, v244
	v_lshlrev_b32_e32 v244, 4, v244
	v_mov_b32_e32 v245, 0
	v_lshrrev_b32_e32 v243, 3, v0
	v_lshlrev_b32_e32 v246, 4, v0
	s_nop 0
	v_readfirstlane_b32 s4, v246
	v_add_u32_e32 v246, s19, v243
	v_mov_b32_e32 v247, 0
	v_lshlrev_b64 v[246:247], 11, v[246:247]
	v_lshl_add_u64 v[246:247], s[52:53], 0, v[246:247]
	v_lshl_add_u64 v[246:247], v[246:247], 0, v[244:245]
	s_mov_b32 s2, s0
	v_add_u32_e32 v243, s2, v243
	s_mov_b64 s[2:3], 0x20000
	s_mov_b32 m0, s4
	s_nop 0
	global_load_lds_dwordx4 v[246:247], off
	s_add_i32 m0, s4, 0x2000
	v_lshl_add_u64 v[246:247], v[246:247], 0, s[2:3]
	global_load_lds_dwordx4 v[246:247], off
	s_add_i32 m0, s4, 0x4000
	v_lshl_add_u64 v[246:247], v[246:247], 0, s[2:3]
	global_load_lds_dwordx4 v[246:247], off
	s_add_i32 m0, s4, 0x6000
	v_lshl_add_u64 v[246:247], v[246:247], 0, s[2:3]
	global_load_lds_dwordx4 v[246:247], off
	v_mov_b32_e32 v246, v243
	v_mov_b32_e32 v247, 0
	v_lshlrev_b64 v[246:247], 11, v[246:247]
	v_lshl_add_u64 v[246:247], s[74:75], 0, v[246:247]
	v_lshl_add_u64 v[246:247], v[246:247], 0, v[244:245]
	s_add_i32 m0, s4, 0x8000
	s_nop 0
	global_load_lds_dwordx4 v[246:247], off
	s_add_i32 m0, s4, 0xa000
	v_lshl_add_u64 v[246:247], v[246:247], 0, s[2:3]
	global_load_lds_dwordx4 v[246:247], off
	s_add_i32 m0, s4, 0xc000
	v_lshl_add_u64 v[246:247], v[246:247], 0, s[2:3]
	global_load_lds_dwordx4 v[246:247], off
	s_add_i32 m0, s4, 0xe000
	v_lshl_add_u64 v[246:247], v[246:247], 0, s[2:3]
	global_load_lds_dwordx4 v[246:247], off
	s_and_saveexec_b64 s[2:3], vcc
	s_xor_b64 s[2:3], exec, s[2:3]
	s_cbranch_execz .LBB0_279
	s_add_i32 s4, s19, 0xfffff000
	s_lshr_b32 s4, s4, 10
	s_mulk_i32 s4, 0xc00
	s_addk_i32 s4, 0xc00
	s_cmp_gt_i32 s1, 15
	s_cselect_b32 s72, s4, 0
	s_lshl_b64 s[4:5], s[72:73], 2
	s_add_u32 s6, s10, s4
	s_addc_u32 s7, s11, s5
	s_ashr_i32 s1, s0, 31
	s_lshl_b64 s[4:5], s[0:1], 2
	s_add_u32 s4, s6, s4
	s_addc_u32 s5, s7, s5
	v_mov_b32_e32 v1, v129
	v_lshl_add_u64 v[2:3], v[0:1], 2, s[4:5]
	v_add_co_u32_e32 v2, vcc, 0xdb000, v2
	s_nop 1
	v_addc_co_u32_e32 v3, vcc, 0, v3, vcc
	global_load_dword v1, v[2:3], off offset:3072

.LBB0_281:
	s_or_b64 exec, exec, s[2:3]
	v_ashrrev_i32_e32 v2, 6, v0
	v_lshrrev_b32_e32 v3, 31, v0
	v_add_u32_e32 v12, v2, v3
	v_and_b32_e32 v3, 0x1fffffe, v12
	v_ashrrev_i32_e32 v6, 3, v0
	v_sub_u32_e32 v13, v2, v3
	v_lshrrev_b32_e32 v14, 4, v0
	v_add_u32_e32 v2, s19, v6
	v_xor_b32_e32 v7, v14, v0
	v_ashrrev_i32_e32 v3, 31, v2
	v_lshlrev_b64 v[2:3], 11, v[2:3]
	v_lshlrev_b32_e32 v7, 4, v7
	v_lshl_add_u32 v10, v0, 2, v167
	v_lshlrev_b32_e32 v146, 4, v0
	v_lshl_add_u64 v[4:5], s[52:53], 0, v[2:3]
	v_and_b32_e32 v128, 0x70, v7
	s_waitcnt vmcnt(0)
	ds_write_b32 v10, v1
	v_readfirstlane_b32 s1, v146
	v_add_u32_e32 v1, 0x2000, v146
	v_lshl_add_u64 v[4:5], v[4:5], 0, v[128:129]
	v_add_u32_e32 v6, s0, v6
	s_mov_b32 m0, s1
	s_mov_b64 s[2:3], 0x20000
	v_readfirstlane_b32 s1, v1
	v_add_u32_e32 v1, 0x4000, v146
	v_ashrrev_i32_e32 v7, 31, v6
	v_lshl_add_u64 v[10:11], v[4:5], 0, s[2:3]
	s_mov_b32 m0, s1
	s_mov_b64 s[4:5], 0x40000
	v_readfirstlane_b32 s1, v1
	v_add_u32_e32 v1, 0x6000, v146
	v_lshlrev_b64 v[6:7], 11, v[6:7]
	v_lshl_add_u64 v[10:11], v[4:5], 0, s[4:5]
	s_mov_b32 m0, s1
	s_mov_b64 s[6:7], 0x60000
	v_readfirstlane_b32 s1, v1
	v_add_u32_e32 v1, 0x8000, v146
	v_lshl_add_u64 v[8:9], s[74:75], 0, v[6:7]
	v_lshl_add_u64 v[4:5], v[4:5], 0, s[6:7]
	s_mov_b32 m0, s1
	v_readfirstlane_b32 s1, v1
	v_add_u32_e32 v1, 0xa000, v146
	v_lshl_add_u64 v[8:9], v[8:9], 0, v[128:129]
	s_mov_b32 m0, s1
	v_readfirstlane_b32 s1, v1
	v_add_u32_e32 v1, 0xc000, v146
	v_lshl_add_u64 v[4:5], v[8:9], 0, s[2:3]
	s_mov_b32 m0, s1
	v_readfirstlane_b32 s1, v1
	v_add_u32_e32 v1, 0xe000, v146
	v_lshl_add_u64 v[4:5], v[8:9], 0, s[4:5]
	s_mov_b32 m0, s1
	v_readfirstlane_b32 s1, v1
	v_lshl_add_u64 v[4:5], v[8:9], 0, s[6:7]
	s_mov_b32 m0, s1
	v_and_b32_e32 v136, 31, v0
	v_bfe_u32 v135, v0, 5, 1
	v_lshrrev_b32_e32 v1, 1, v0
	v_lshlrev_b32_e32 v128, 7, v13
	v_bfe_u32 v4, v0, 1, 3
	v_or_b32_e32 v5, v128, v136
	v_bitop3_b32 v1, v135, v1, 7 bitop3:0x78
	v_and_b32_e32 v134, 63, v0
	v_lshlrev_b32_e32 v149, 7, v5
	v_lshlrev_b32_e32 v5, 5, v12
	v_lshlrev_b32_e32 v148, 4, v1
	v_bitop3_b32 v1, v135, v4, 2 bitop3:0x36
	v_bitop3_b32 v0, v14, 7, v0 bitop3:0x48
	v_and_b32_e32 v137, 0xffffffc0, v5
	v_lshlrev_b32_e32 v147, 4, v1
	v_bitop3_b32 v1, v135, v4, 4 bitop3:0x36
	v_lshlrev_b32_e32 v0, 4, v0
	v_or_b32_e32 v5, v137, v136
	v_lshlrev_b32_e32 v145, 4, v1
	v_bitop3_b32 v1, v135, v4, 6 bitop3:0x36
	v_or_b32_e32 v6, v6, v0
	v_or_b32_e32 v2, v2, v0
	v_mov_b32_e32 v32, 0
	v_lshlrev_b32_e32 v150, 7, v5
	v_lshlrev_b32_e32 v144, 4, v1
	v_add_u32_e32 v151, 0x8000, v149
	v_lshl_add_u64 v[130:131], s[82:83], 0, v[6:7]
	v_lshl_add_u64 v[132:133], s[50:51], 0, v[2:3]
	s_mov_b32 s1, 0
	s_mov_b64 s[2:3], 0
	v_mov_b32_e32 v33, v32
	v_mov_b32_e32 v34, v32
	v_mov_b32_e32 v35, v32
	v_mov_b32_e32 v36, v32
	v_mov_b32_e32 v37, v32
	v_mov_b32_e32 v38, v32
	v_mov_b32_e32 v39, v32
	v_mov_b32_e32 v40, v32
	v_mov_b32_e32 v41, v32
	v_mov_b32_e32 v42, v32
	v_mov_b32_e32 v43, v32
	v_mov_b32_e32 v44, v32
	v_mov_b32_e32 v45, v32
	v_mov_b32_e32 v46, v32
	v_mov_b32_e32 v47, v32
	v_mov_b32_e32 v96, v32
	v_mov_b32_e32 v97, v32
	v_mov_b32_e32 v98, v32
	v_mov_b32_e32 v99, v32
	v_mov_b32_e32 v100, v32
	v_mov_b32_e32 v101, v32
	v_mov_b32_e32 v102, v32
	v_mov_b32_e32 v103, v32
	v_mov_b32_e32 v104, v32
	v_mov_b32_e32 v105, v32
	v_mov_b32_e32 v106, v32
	v_mov_b32_e32 v107, v32
	v_mov_b32_e32 v108, v32
	v_mov_b32_e32 v109, v32
	v_mov_b32_e32 v110, v32
	v_mov_b32_e32 v111, v32
	v_mov_b32_e32 v48, v32
	v_mov_b32_e32 v49, v32
	v_mov_b32_e32 v50, v32
	v_mov_b32_e32 v51, v32
	v_mov_b32_e32 v52, v32
	v_mov_b32_e32 v53, v32
	v_mov_b32_e32 v54, v32
	v_mov_b32_e32 v55, v32
	v_mov_b32_e32 v56, v32
	v_mov_b32_e32 v57, v32
	v_mov_b32_e32 v58, v32
	v_mov_b32_e32 v59, v32
	v_mov_b32_e32 v60, v32
	v_mov_b32_e32 v61, v32
	v_mov_b32_e32 v62, v32
	v_mov_b32_e32 v63, v32
	v_mov_b32_e32 v112, v32
	v_mov_b32_e32 v113, v32
	v_mov_b32_e32 v114, v32
	v_mov_b32_e32 v115, v32
	v_mov_b32_e32 v116, v32
	v_mov_b32_e32 v117, v32
	v_mov_b32_e32 v118, v32
	v_mov_b32_e32 v119, v32
	v_mov_b32_e32 v120, v32
	v_mov_b32_e32 v121, v32
	v_mov_b32_e32 v122, v32
	v_mov_b32_e32 v123, v32
	v_mov_b32_e32 v124, v32
	v_mov_b32_e32 v125, v32
	v_mov_b32_e32 v126, v32
	v_mov_b32_e32 v127, v32
	v_mov_b32_e32 v80, v32
	v_mov_b32_e32 v81, v32
	v_mov_b32_e32 v82, v32
	v_mov_b32_e32 v83, v32
	v_mov_b32_e32 v84, v32
	v_mov_b32_e32 v85, v32
	v_mov_b32_e32 v86, v32
	v_mov_b32_e32 v87, v32
	v_mov_b32_e32 v88, v32
	v_mov_b32_e32 v89, v32
	v_mov_b32_e32 v90, v32
	v_mov_b32_e32 v91, v32
	v_mov_b32_e32 v92, v32
	v_mov_b32_e32 v93, v32
	v_mov_b32_e32 v94, v32
	v_mov_b32_e32 v95, v32
	v_mov_b32_e32 v16, v32
	v_mov_b32_e32 v17, v32
	v_mov_b32_e32 v18, v32
	v_mov_b32_e32 v19, v32
	v_mov_b32_e32 v20, v32
	v_mov_b32_e32 v21, v32
	v_mov_b32_e32 v22, v32
	v_mov_b32_e32 v23, v32
	v_mov_b32_e32 v24, v32
	v_mov_b32_e32 v25, v32
	v_mov_b32_e32 v26, v32
	v_mov_b32_e32 v27, v32
	v_mov_b32_e32 v28, v32
	v_mov_b32_e32 v29, v32
	v_mov_b32_e32 v30, v32
	v_mov_b32_e32 v31, v32
	v_mov_b32_e32 v64, v32
	v_mov_b32_e32 v65, v32
	v_mov_b32_e32 v66, v32
	v_mov_b32_e32 v67, v32
	v_mov_b32_e32 v68, v32
	v_mov_b32_e32 v69, v32
	v_mov_b32_e32 v70, v32
	v_mov_b32_e32 v71, v32
	v_mov_b32_e32 v72, v32
	v_mov_b32_e32 v73, v32
	v_mov_b32_e32 v74, v32
	v_mov_b32_e32 v75, v32
	v_mov_b32_e32 v76, v32
	v_mov_b32_e32 v77, v32
	v_mov_b32_e32 v78, v32
	v_mov_b32_e32 v79, v32
	v_mov_b32_e32 v0, v32
	v_mov_b32_e32 v1, v32
	v_mov_b32_e32 v2, v32
	v_mov_b32_e32 v3, v32
	v_mov_b32_e32 v4, v32
	v_mov_b32_e32 v5, v32
	v_mov_b32_e32 v6, v32
	v_mov_b32_e32 v7, v32
	v_mov_b32_e32 v8, v32
	v_mov_b32_e32 v9, v32
	v_mov_b32_e32 v10, v32
	v_mov_b32_e32 v11, v32
	v_mov_b32_e32 v12, v32
	v_mov_b32_e32 v13, v32
	v_mov_b32_e32 v14, v32
	v_mov_b32_e32 v15, v32
	s_mov_b64 s[8:9], 0x6fb4080
	s_mov_b64 s[12:13], 0x6fd4080
	s_mov_b64 s[14:15], 0x6ff4080

.LBB0_678:
	s_ashr_i32 s0, s6, 31
	s_lshr_b32 s0, s0, 26
	s_add_i32 s0, s6, s0
	s_and_b32 s1, s0, 0xffffffc0
	s_sub_i32 s5, s6, s1
	s_mul_i32 s4, s5, 0xc0
	s_lshl_b32 s2, s0, 2
	v_mov_b32_e32 v100, v155
	s_add_i32 s0, s4, 0xbf
	v_mov_b32_e32 v0, s0
	v_mov_b32_e32 v1, s4
	v_cmp_gt_i32_e32 vcc, s31, v100
	s_movk_i32 s0, 0x1800
	s_nop 0
	v_cndmask_b32_e32 v1, v0, v1, vcc
	v_add_u32_e32 v0, 0xfffff000, v1
	v_lshrrev_b32_e32 v2, 10, v0
	v_mad_u32_u24 v2, v2, s0, s0
	s_movk_i32 s0, 0xfff
	v_mov_b32_e32 v0, s2
	v_cmp_lt_i32_e32 vcc, s0, v1
	v_bfi_b32 v0, s39, v100, v0
	v_ashrrev_i32_e32 v1, 31, v0
	v_cndmask_b32_e32 v128, 0, v2, vcc
	v_lshl_add_u64 v[2:3], v[128:129], 2, s[54:55]
	v_lshl_add_u64 v[2:3], v[0:1], 2, v[2:3]
	s_barrier
	v_lshrrev_b32_e32 v244, 4, v100
	v_xor_b32_e32 v244, v244, v100
	v_and_b32_e32 v244, 7, v244
	v_lshlrev_b32_e32 v244, 4, v244
	v_mov_b32_e32 v245, 0
	v_lshrrev_b32_e32 v243, 3, v100
	v_lshlrev_b32_e32 v246, 4, v100
	s_nop 0
	v_readfirstlane_b32 s3, v246
	v_add_u32_e32 v246, s4, v243
	v_mov_b32_e32 v247, 0
	v_lshlrev_b64 v[246:247], 11, v[246:247]
	v_lshl_add_u64 v[246:247], s[50:51], 0, v[246:247]
	v_lshl_add_u64 v[246:247], v[246:247], 0, v[244:245]
	s_and_b32 s0, s2, 0xffffff00
	v_add_u32_e32 v243, s0, v243
	s_mov_b64 s[0:1], 0x20000
	s_mov_b32 m0, s3
	s_nop 0
	global_load_lds_dwordx4 v[246:247], off
	s_add_i32 m0, s3, 0x2000
	v_lshl_add_u64 v[246:247], v[246:247], 0, s[0:1]
	global_load_lds_dwordx4 v[246:247], off
	s_add_i32 m0, s3, 0x4000
	v_lshl_add_u64 v[246:247], v[246:247], 0, s[0:1]
	global_load_lds_dwordx4 v[246:247], off
	v_mov_b32_e32 v246, v243
	v_mov_b32_e32 v247, 0
	v_lshlrev_b64 v[246:247], 11, v[246:247]
	v_lshl_add_u64 v[246:247], s[60:61], 0, v[246:247]
	v_lshl_add_u64 v[246:247], v[246:247], 0, v[244:245]
	s_add_i32 m0, s3, 0x6000
	s_nop 0
	global_load_lds_dwordx4 v[246:247], off
	s_add_i32 m0, s3, 0x8000
	v_lshl_add_u64 v[246:247], v[246:247], 0, s[0:1]
	global_load_lds_dwordx4 v[246:247], off
	s_add_i32 m0, s3, 0xa000
	v_lshl_add_u64 v[246:247], v[246:247], 0, s[0:1]
	global_load_lds_dwordx4 v[246:247], off
	s_add_i32 m0, s3, 0xc000
	v_lshl_add_u64 v[246:247], v[246:247], 0, s[0:1]
	global_load_lds_dwordx4 v[246:247], off
	global_load_dword v3, v[2:3], off
	v_readlane_b32 s8, v241, 20
	v_readlane_b32 s9, v241, 21
	v_mov_b32_e32 v32, 0
	s_andn2_b64 vcc, exec, s[8:9]
	v_cndmask_b32_e64 v2, 0, 1, s[8:9]
	v_cmp_ne_u32_e64 s[0:1], 1, v2
	v_lshl_add_u32 v2, v100, 2, v167
	s_waitcnt vmcnt(0)
	ds_write_b32 v2, v3
	v_mov_b32_e32 v3, 0
	s_cbranch_vccnz .LBB0_680
	v_lshl_add_u64 v[4:5], v[128:129], 2, s[58:59]
	v_lshlrev_b64 v[0:1], 2, v[0:1]
	v_lshl_add_u64 v[4:5], v[4:5], 0, v[0:1]
	v_lshl_add_u64 v[0:1], s[56:57], 0, v[0:1]
	global_load_dword v3, v[4:5], off
	s_nop 0
	global_load_dword v0, v[0:1], off
	s_waitcnt vmcnt(1)
	v_add_f32_e32 v1, 1.0, v3
	s_waitcnt vmcnt(0)
	v_mul_f32_e32 v3, v0, v1
.LBB0_680:
	v_ashrrev_i32_e32 v103, 6, v100
	v_lshrrev_b32_e32 v0, 30, v103
	v_add_u32_e32 v0, v103, v0
	v_ashrrev_i32_e32 v10, 2, v0
	v_mul_i32_i24_e32 v0, 4, v10
	v_ashrrev_i32_e32 v6, 3, v100
	v_sub_u32_e32 v11, v103, v0
	v_lshrrev_b32_e32 v13, 4, v100
	v_add_u32_e32 v0, s4, v6
	v_xor_b32_e32 v7, v13, v100
	v_ashrrev_i32_e32 v1, 31, v0
	v_lshlrev_b64 v[0:1], 11, v[0:1]
	v_lshlrev_b32_e32 v7, 4, v7
	v_lshlrev_b32_e32 v109, 4, v100
	s_and_b32 s8, s2, 0xffffff00
	v_lshl_add_u64 v[4:5], s[50:51], 0, v[0:1]
	v_and_b32_e32 v128, 0x70, v7
	v_readfirstlane_b32 s2, v109
	v_add_u32_e32 v14, 0x2000, v109
	v_lshl_add_u64 v[4:5], v[4:5], 0, v[128:129]
	s_mov_b32 m0, s2
	s_mov_b64 s[10:11], 0x20000
	v_readfirstlane_b32 s2, v14
	ds_write_b32 v2, v3 offset:2048
	v_lshl_add_u64 v[2:3], v[4:5], 0, s[10:11]
	s_mov_b32 m0, s2
	s_mov_b64 s[12:13], 0x40000
	v_lshl_add_u64 v[2:3], v[4:5], 0, s[12:13]
	v_add_u32_e32 v4, 0x4000, v109
	v_add_u32_e32 v6, s8, v6
	v_readfirstlane_b32 s2, v4
	v_ashrrev_i32_e32 v7, 31, v6
	s_mov_b32 m0, s2
	v_lshlrev_b64 v[6:7], 11, v[6:7]
	v_add_u32_e32 v2, 0x6000, v109
	v_lshl_add_u64 v[8:9], s[60:61], 0, v[6:7]
	v_readfirstlane_b32 s2, v2
	v_add_u32_e32 v4, 0x8000, v109
	v_lshl_add_u64 v[8:9], v[8:9], 0, v[128:129]
	s_mov_b32 m0, s2
	v_readfirstlane_b32 s2, v4
	v_add_u32_e32 v4, 0xa000, v109
	v_lshl_add_u64 v[2:3], v[8:9], 0, s[10:11]
	s_mov_b32 m0, s2
	v_readfirstlane_b32 s2, v4
	v_lshl_add_u64 v[2:3], v[8:9], 0, s[12:13]
	s_mov_b32 m0, s2
	s_mov_b64 s[2:3], 0x60000
	v_add_u32_e32 v4, 0xc000, v109
	v_lshl_add_u64 v[2:3], v[8:9], 0, s[2:3]
	v_readfirstlane_b32 s2, v4
	s_mov_b32 m0, s2
	v_and_b32_e32 v102, 31, v100
	v_lshlrev_b32_e32 v105, 6, v11
	v_or_b32_e32 v3, v105, v102
	v_mul_i32_i24_e32 v106, 0x60, v10
	v_bfe_u32 v12, v100, 5, 1
	v_lshrrev_b32_e32 v104, 1, v100
	v_lshlrev_b32_e32 v112, 7, v3
	v_or_b32_e32 v3, v106, v102
	v_bfe_u32 v2, v100, 1, 3
	v_lshlrev_b32_e32 v113, 7, v3
	v_bitop3_b32 v3, v12, v104, 7 bitop3:0x78
	v_lshlrev_b32_e32 v111, 4, v3
	v_bitop3_b32 v3, v12, v2, 2 bitop3:0x36
	v_lshlrev_b32_e32 v110, 4, v3
	v_bitop3_b32 v3, v12, v2, 4 bitop3:0x36
	v_bitop3_b32 v2, v12, v2, 6 bitop3:0x36
	v_lshlrev_b32_e32 v107, 4, v2
	v_bitop3_b32 v2, v13, 7, v100 bitop3:0x48
	v_lshlrev_b32_e32 v2, 4, v2
	v_or_b32_e32 v6, v6, v2
	v_or_b32_e32 v0, v0, v2
	v_and_b32_e32 v101, 63, v100
	v_lshlrev_b32_e32 v108, 4, v3
	v_add_u32_e32 v114, 0x6000, v112
	v_lshl_add_u64 v[96:97], s[62:63], 0, v[6:7]
	v_lshl_add_u64 v[98:99], s[14:15], 0, v[0:1]
	s_mov_b32 s7, 0
	s_mov_b64 s[2:3], 0
	v_mov_b32_e32 v33, v32
	v_mov_b32_e32 v34, v32
	v_mov_b32_e32 v35, v32
	v_mov_b32_e32 v36, v32
	v_mov_b32_e32 v37, v32
	v_mov_b32_e32 v38, v32
	v_mov_b32_e32 v39, v32
	v_mov_b32_e32 v40, v32
	v_mov_b32_e32 v41, v32
	v_mov_b32_e32 v42, v32
	v_mov_b32_e32 v43, v32
	v_mov_b32_e32 v44, v32
	v_mov_b32_e32 v45, v32
	v_mov_b32_e32 v46, v32
	v_mov_b32_e32 v47, v32
	v_mov_b32_e32 v64, v32
	v_mov_b32_e32 v65, v32
	v_mov_b32_e32 v66, v32
	v_mov_b32_e32 v67, v32
	v_mov_b32_e32 v68, v32
	v_mov_b32_e32 v69, v32
	v_mov_b32_e32 v70, v32
	v_mov_b32_e32 v71, v32
	v_mov_b32_e32 v72, v32
	v_mov_b32_e32 v73, v32
	v_mov_b32_e32 v74, v32
	v_mov_b32_e32 v75, v32
	v_mov_b32_e32 v76, v32
	v_mov_b32_e32 v77, v32
	v_mov_b32_e32 v78, v32
	v_mov_b32_e32 v79, v32
	v_mov_b32_e32 v0, v32
	v_mov_b32_e32 v1, v32
	v_mov_b32_e32 v2, v32
	v_mov_b32_e32 v3, v32
	v_mov_b32_e32 v4, v32
	v_mov_b32_e32 v5, v32
	v_mov_b32_e32 v6, v32
	v_mov_b32_e32 v7, v32
	v_mov_b32_e32 v8, v32
	v_mov_b32_e32 v9, v32
	v_mov_b32_e32 v10, v32
	v_mov_b32_e32 v11, v32
	v_mov_b32_e32 v12, v32
	v_mov_b32_e32 v13, v32
	v_mov_b32_e32 v14, v32
	v_mov_b32_e32 v15, v32
	v_mov_b32_e32 v80, v32
	v_mov_b32_e32 v81, v32
	v_mov_b32_e32 v82, v32
	v_mov_b32_e32 v83, v32
	v_mov_b32_e32 v84, v32
	v_mov_b32_e32 v85, v32
	v_mov_b32_e32 v86, v32
	v_mov_b32_e32 v87, v32
	v_mov_b32_e32 v88, v32
	v_mov_b32_e32 v89, v32
	v_mov_b32_e32 v90, v32
	v_mov_b32_e32 v91, v32
	v_mov_b32_e32 v92, v32
	v_mov_b32_e32 v93, v32
	v_mov_b32_e32 v94, v32
	v_mov_b32_e32 v95, v32
	v_mov_b32_e32 v48, v32
	v_mov_b32_e32 v49, v32
	v_mov_b32_e32 v50, v32
	v_mov_b32_e32 v51, v32
	v_mov_b32_e32 v52, v32
	v_mov_b32_e32 v53, v32
	v_mov_b32_e32 v54, v32
	v_mov_b32_e32 v55, v32
	v_mov_b32_e32 v56, v32
	v_mov_b32_e32 v57, v32
	v_mov_b32_e32 v58, v32
	v_mov_b32_e32 v59, v32
	v_mov_b32_e32 v60, v32
	v_mov_b32_e32 v61, v32
	v_mov_b32_e32 v62, v32
	v_mov_b32_e32 v63, v32
	v_mov_b32_e32 v16, v32
	v_mov_b32_e32 v17, v32
	v_mov_b32_e32 v18, v32
	v_mov_b32_e32 v19, v32
	v_mov_b32_e32 v20, v32
	v_mov_b32_e32 v21, v32
	v_mov_b32_e32 v22, v32
	v_mov_b32_e32 v23, v32
	v_mov_b32_e32 v24, v32
	v_mov_b32_e32 v25, v32
	v_mov_b32_e32 v26, v32
	v_mov_b32_e32 v27, v32
	v_mov_b32_e32 v28, v32
	v_mov_b32_e32 v29, v32
	v_mov_b32_e32 v30, v32
	v_mov_b32_e32 v31, v32
	s_mov_b64 s[12:13], 0x8794080
	s_mov_b64 s[16:17], 0x87b4080
	s_mov_b64 s[18:19], 0x87d4080

.LBB0_830:
	s_ashr_i32 s0, s12, 31
	s_lshr_b32 s0, s0, 26
	s_add_i32 s2, s12, s0
	s_and_b32 s0, s2, 0xffffffc0
	s_sub_i32 s4, s12, s0
	v_mov_b32_e32 v4, v155
	s_movk_i32 s0, 0xc0
	s_mul_i32 s26, s4, 0xc0
	s_nop 0
	v_cmp_gt_i32_e32 vcc, s0, v4
	s_barrier
	v_lshrrev_b32_e32 v244, 4, v4
	v_xor_b32_e32 v244, v244, v4
	v_and_b32_e32 v244, 7, v244
	v_lshlrev_b32_e32 v244, 4, v244
	v_mov_b32_e32 v245, 0
	v_lshrrev_b32_e32 v243, 3, v4
	v_lshlrev_b32_e32 v246, 4, v4
	s_nop 0
	v_readfirstlane_b32 s3, v246
	v_add_u32_e32 v246, s26, v243
	v_mov_b32_e32 v247, 0
	v_lshlrev_b64 v[246:247], 11, v[246:247]
	v_lshl_add_u64 v[246:247], s[52:53], 0, v[246:247]
	v_lshl_add_u64 v[246:247], v[246:247], 0, v[244:245]
	s_ashr_i32 s0, s2, 6
	s_lshl_b32 s0, s0, 8
	v_add_u32_e32 v243, s0, v243
	s_mov_b64 s[0:1], 0x20000
	s_mov_b32 m0, s3
	s_nop 0
	global_load_lds_dwordx4 v[246:247], off
	s_add_i32 m0, s3, 0x2000
	v_lshl_add_u64 v[246:247], v[246:247], 0, s[0:1]
	global_load_lds_dwordx4 v[246:247], off
	s_add_i32 m0, s3, 0x4000
	v_lshl_add_u64 v[246:247], v[246:247], 0, s[0:1]
	global_load_lds_dwordx4 v[246:247], off
	v_mov_b32_e32 v246, v243
	v_mov_b32_e32 v247, 0
	v_lshlrev_b64 v[246:247], 11, v[246:247]
	v_lshl_add_u64 v[246:247], s[64:65], 0, v[246:247]
	v_lshl_add_u64 v[246:247], v[246:247], 0, v[244:245]
	s_add_i32 m0, s3, 0x6000
	s_nop 0
	global_load_lds_dwordx4 v[246:247], off
	s_add_i32 m0, s3, 0x8000
	v_lshl_add_u64 v[246:247], v[246:247], 0, s[0:1]
	global_load_lds_dwordx4 v[246:247], off
	s_add_i32 m0, s3, 0xa000
	v_lshl_add_u64 v[246:247], v[246:247], 0, s[0:1]
	global_load_lds_dwordx4 v[246:247], off
	s_add_i32 m0, s3, 0xc000
	v_lshl_add_u64 v[246:247], v[246:247], 0, s[0:1]
	global_load_lds_dwordx4 v[246:247], off
	s_and_saveexec_b64 s[0:1], vcc
	s_cbranch_execz .LBB0_832
	v_add_u32_e32 v0, s26, v4
	v_ashrrev_i32_e32 v1, 31, v0
	v_lshl_add_u64 v[0:1], v[0:1], 2, s[54:55]
	v_add_co_u32_e32 v2, vcc, 0xc000, v0
	global_load_dword v5, v[0:1], off
	s_nop 0
	v_addc_co_u32_e32 v3, vcc, 0, v1, vcc
	global_load_dword v6, v[2:3], off
	v_add_co_u32_e32 v2, vcc, 0x18000, v0
	s_mov_b32 s3, 0x800000
	s_nop 0
	v_addc_co_u32_e32 v3, vcc, 0, v1, vcc
	global_load_dword v7, v[2:3], off
	v_add_co_u32_e32 v2, vcc, 0x24000, v0
	s_nop 1
	v_addc_co_u32_e32 v3, vcc, 0, v1, vcc
	global_load_dword v8, v[2:3], off
	v_add_co_u32_e32 v2, vcc, 0x30000, v0
	s_nop 1
	v_addc_co_u32_e32 v3, vcc, 0, v1, vcc
	global_load_dword v9, v[2:3], off
	v_add_co_u32_e32 v2, vcc, 0x3c000, v0
	s_nop 1
	v_addc_co_u32_e32 v3, vcc, 0, v1, vcc
	global_load_dword v10, v[2:3], off
	v_add_co_u32_e32 v2, vcc, 0x48000, v0
	s_nop 1
	v_addc_co_u32_e32 v3, vcc, 0, v1, vcc
	global_load_dword v11, v[2:3], off
	v_add_co_u32_e32 v2, vcc, 0x54000, v0
	s_nop 1
	v_addc_co_u32_e32 v3, vcc, 0, v1, vcc
	global_load_dword v12, v[2:3], off
	v_add_co_u32_e32 v2, vcc, 0x60000, v0
	s_nop 1
	v_addc_co_u32_e32 v3, vcc, 0, v1, vcc
	global_load_dword v13, v[2:3], off
	v_add_co_u32_e32 v2, vcc, 0x6c000, v0
	s_nop 1
	v_addc_co_u32_e32 v3, vcc, 0, v1, vcc
	global_load_dword v14, v[2:3], off
	v_add_co_u32_e32 v2, vcc, 0x78000, v0
	s_nop 1
	v_addc_co_u32_e32 v3, vcc, 0, v1, vcc
	global_load_dword v15, v[2:3], off
	v_add_co_u32_e32 v2, vcc, 0x84000, v0
	s_nop 1
	v_addc_co_u32_e32 v3, vcc, 0, v1, vcc
	global_load_dword v16, v[2:3], off
	v_add_co_u32_e32 v2, vcc, 0x90000, v0
	s_nop 1
	v_addc_co_u32_e32 v3, vcc, 0, v1, vcc
	global_load_dword v17, v[2:3], off
	v_add_co_u32_e32 v2, vcc, 0x9c000, v0
	s_nop 1
	v_addc_co_u32_e32 v3, vcc, 0, v1, vcc
	global_load_dword v18, v[2:3], off
	v_add_co_u32_e32 v2, vcc, 0xa8000, v0
	s_nop 1
	v_addc_co_u32_e32 v3, vcc, 0, v1, vcc
	v_add_co_u32_e32 v0, vcc, 0xb4000, v0
	global_load_dword v2, v[2:3], off
	s_nop 0
	v_addc_co_u32_e32 v1, vcc, 0, v1, vcc
	global_load_dword v0, v[0:1], off
	s_waitcnt vmcnt(15)
	v_add_f32_e32 v1, 0, v5
	s_waitcnt vmcnt(14)
	v_add_f32_e32 v1, v1, v6
	s_waitcnt vmcnt(13)
	v_add_f32_e32 v1, v1, v7
	s_waitcnt vmcnt(12)
	v_add_f32_e32 v1, v1, v8
	s_waitcnt vmcnt(11)
	v_add_f32_e32 v1, v1, v9
	s_waitcnt vmcnt(10)
	v_add_f32_e32 v1, v1, v10
	s_waitcnt vmcnt(9)
	v_add_f32_e32 v1, v1, v11
	s_waitcnt vmcnt(8)
	v_add_f32_e32 v1, v1, v12
	s_waitcnt vmcnt(7)
	v_add_f32_e32 v1, v1, v13
	s_waitcnt vmcnt(6)
	v_add_f32_e32 v1, v1, v14
	s_waitcnt vmcnt(5)
	v_add_f32_e32 v1, v1, v15
	s_waitcnt vmcnt(4)
	v_add_f32_e32 v1, v1, v16
	s_waitcnt vmcnt(3)
	v_add_f32_e32 v1, v1, v17
	s_waitcnt vmcnt(2)
	v_add_f32_e32 v1, v1, v18
	s_waitcnt vmcnt(1)
	v_add_f32_e32 v1, v1, v2
	s_waitcnt vmcnt(0)
	v_add_f32_e32 v0, v1, v0
	v_fmamk_f32 v0, v0, 0x3a800000, v163
	v_cmp_gt_f32_e32 vcc, s3, v0
	v_mul_f32_e32 v1, 0x4b800000, v0
	s_nop 0
	v_cndmask_b32_e32 v0, v0, v1, vcc
	v_rsq_f32_e32 v0, v0
	s_nop 0
	v_mul_f32_e32 v1, 0x45800000, v0
	v_cndmask_b32_e32 v0, v0, v1, vcc
	v_lshl_add_u32 v1, v4, 2, v167
	ds_write_b32 v1, v0
.LBB0_832:
	s_or_b64 exec, exec, s[0:1]
	v_ashrrev_i32_e32 v0, 6, v4
	v_lshrrev_b32_e32 v1, 30, v0
	v_add_u32_e32 v1, v0, v1
	v_ashrrev_i32_e32 v5, 2, v1
	v_mul_i32_i24_e32 v1, 4, v5
	v_ashrrev_i32_e32 v8, 3, v4
	v_sub_u32_e32 v13, v0, v1
	v_lshrrev_b32_e32 v14, 4, v4
	v_add_u32_e32 v0, s26, v8
	v_xor_b32_e32 v6, v14, v4
	v_ashrrev_i32_e32 v1, 31, v0
	s_add_i32 s1, s26, 0xbf
	s_ashr_i32 s0, s2, 6
	v_lshlrev_b64 v[0:1], 11, v[0:1]
	v_lshlrev_b32_e32 v6, 4, v6
	v_cmp_gt_i32_e32 vcc, s31, v4
	v_mov_b32_e32 v10, s1
	v_mov_b32_e32 v11, s26
	s_lshl_b32 s0, s0, 8
	v_lshl_add_u64 v[2:3], s[52:53], 0, v[0:1]
	v_and_b32_e32 v128, 0x70, v6
	v_cndmask_b32_e32 v10, v10, v11, vcc
	v_lshl_add_u64 v[6:7], v[2:3], 0, v[128:129]
	v_add_u32_e32 v2, s0, v8
	v_add_u32_e32 v11, 0xfffff000, v10
	v_ashrrev_i32_e32 v3, 31, v2
	v_lshrrev_b32_e32 v11, 10, v11
	s_movk_i32 s1, 0xc00
	v_lshlrev_b64 v[2:3], 11, v[2:3]
	v_mad_u32_u24 v11, v11, s1, s1
	s_movk_i32 s1, 0xfff
	v_lshl_add_u64 v[8:9], s[64:65], 0, v[2:3]
	v_cmp_lt_i32_e32 vcc, s1, v10
	v_lshl_add_u64 v[8:9], v[8:9], 0, v[128:129]
	s_ashr_i32 s1, s0, 31
	v_cndmask_b32_e32 v128, 0, v11, vcc
	v_lshl_add_u64 v[10:11], v[128:129], 2, s[56:57]
	v_lshl_add_u64 v[10:11], s[0:1], 2, v[10:11]
	v_lshlrev_b32_sdwa v128, v176, v4 dst_sel:DWORD dst_unused:UNUSED_PAD src0_sel:DWORD src1_sel:BYTE_0
	v_lshl_add_u64 v[10:11], v[10:11], 0, v[128:129]
	global_load_dword v10, v[10:11], off
	v_lshlrev_b32_e32 v102, 4, v4
	v_add_u32_e32 v15, 0x2000, v102
	v_readfirstlane_b32 s1, v102
	v_lshl_add_u32 v11, v4, 2, v177
	s_mov_b32 m0, s1
	s_mov_b64 s[2:3], 0x20000
	v_readfirstlane_b32 s1, v15
	s_mov_b64 s[6:7], 0x40000
	v_and_b32_e32 v101, 31, v4
	v_mul_i32_i24_e32 v104, 0x60, v5
	v_lshrrev_b32_e32 v12, 5, v4
	v_or_b32_e32 v5, v104, v101
	v_bfe_u32 v100, v4, 5, 1
	v_lshlrev_b32_e32 v106, 7, v5
	v_lshlrev_b32_e32 v103, 6, v13
	v_mov_b32_e32 v48, 0
	s_mov_b32 s5, 0
	v_mov_b32_e32 v49, v48
	v_mov_b32_e32 v50, v48
	v_mov_b32_e32 v51, v48
	v_mov_b32_e32 v52, v48
	v_mov_b32_e32 v53, v48
	v_mov_b32_e32 v54, v48
	v_mov_b32_e32 v55, v48
	v_mov_b32_e32 v56, v48
	v_mov_b32_e32 v57, v48
	v_mov_b32_e32 v58, v48
	v_mov_b32_e32 v59, v48
	v_mov_b32_e32 v60, v48
	v_mov_b32_e32 v61, v48
	v_mov_b32_e32 v62, v48
	v_mov_b32_e32 v63, v48
	s_waitcnt vmcnt(10)
	v_mov_b32_e32 v80, v48
	v_mov_b32_e32 v81, v48
	v_mov_b32_e32 v82, v48
	v_mov_b32_e32 v83, v48
	s_waitcnt vmcnt(9)
	v_mov_b32_e32 v84, v48
	v_mov_b32_e32 v85, v48
	v_mov_b32_e32 v86, v48
	v_mov_b32_e32 v87, v48
	v_mov_b32_e32 v88, v48
	v_mov_b32_e32 v89, v48
	v_mov_b32_e32 v90, v48
	v_mov_b32_e32 v91, v48
	v_mov_b32_e32 v92, v48
	v_mov_b32_e32 v93, v48
	v_mov_b32_e32 v94, v48
	v_mov_b32_e32 v95, v48
	v_mov_b32_e32 v13, v48
	v_mov_b32_e32 v15, v48
	v_mov_b32_e32 v64, v48
	v_mov_b32_e32 v65, v48
	v_mov_b32_e32 v66, v48
	v_mov_b32_e32 v67, v48
	v_mov_b32_e32 v68, v48
	v_mov_b32_e32 v69, v48
	v_mov_b32_e32 v70, v48
	v_mov_b32_e32 v71, v48
	v_mov_b32_e32 v72, v48
	v_mov_b32_e32 v73, v48
	v_mov_b32_e32 v74, v48
	v_mov_b32_e32 v75, v48
	v_mov_b32_e32 v76, v48
	v_mov_b32_e32 v77, v48
	v_mov_b32_e32 v78, v48
	v_mov_b32_e32 v79, v48
	v_mov_b32_e32 v32, v48
	v_mov_b32_e32 v33, v48
	v_mov_b32_e32 v34, v48
	v_mov_b32_e32 v35, v48
	v_mov_b32_e32 v36, v48
	v_mov_b32_e32 v37, v48
	v_mov_b32_e32 v38, v48
	v_mov_b32_e32 v39, v48
	v_mov_b32_e32 v40, v48
	v_mov_b32_e32 v41, v48
	v_mov_b32_e32 v42, v48
	v_mov_b32_e32 v43, v48
	v_mov_b32_e32 v44, v48
	s_waitcnt vmcnt(0)
	ds_write_b32 v11, v10
	v_lshl_add_u64 v[10:11], v[6:7], 0, s[2:3]
	s_mov_b32 m0, s1
	v_lshl_add_u64 v[6:7], v[6:7], 0, s[6:7]
	v_add_u32_e32 v10, 0x4000, v102
	v_mov_b32_e32 v11, v48
	v_readfirstlane_b32 s1, v10
	s_mov_b32 m0, s1
	v_add_u32_e32 v10, 0x8000, v102
	v_add_u32_e32 v6, 0x6000, v102
	v_mov_b32_e32 v45, v48
	v_readfirstlane_b32 s1, v6
	s_mov_b32 m0, s1
	v_readfirstlane_b32 s1, v10
	v_add_u32_e32 v10, 0xa000, v102
	v_lshl_add_u64 v[6:7], v[8:9], 0, s[2:3]
	s_mov_b32 m0, s1
	v_readfirstlane_b32 s1, v10
	v_lshl_add_u64 v[6:7], v[8:9], 0, s[6:7]
	s_mov_b32 m0, s1
	s_mov_b64 s[2:3], 0x60000
	v_lshl_add_u64 v[6:7], v[8:9], 0, s[2:3]
	v_add_u32_e32 v8, 0xc000, v102
	s_mov_b64 s[2:3], 0
	v_readfirstlane_b32 s1, v8
	s_mov_b32 m0, s1
	v_mov_b32_e32 v8, v48
	v_bfe_u32 v6, v4, 1, 3
	v_bitop3_b32 v5, v12, v6, 1 bitop3:0x6c
	v_lshlrev_b32_e32 v108, 4, v5
	v_bitop3_b32 v5, v100, v6, 2 bitop3:0x36
	v_bitop3_b32 v4, v14, 7, v4 bitop3:0x48
	v_or_b32_e32 v7, v103, v101
	v_lshlrev_b32_e32 v107, 4, v5
	v_bitop3_b32 v5, v100, v6, 4 bitop3:0x36
	v_lshlrev_b32_e32 v4, 4, v4
	v_lshlrev_b32_e32 v105, 7, v7
	v_lshlrev_b32_e32 v110, 4, v5
	v_bitop3_b32 v5, v100, v6, 6 bitop3:0x36
	v_or_b32_e32 v2, v2, v4
	v_or_b32_e32 v0, v0, v4
	v_lshlrev_b32_e32 v109, 4, v5
	v_add_u32_e32 v111, 0x6000, v105
	v_lshl_add_u64 v[96:97], s[66:67], 0, v[2:3]
	v_lshl_add_u64 v[98:99], s[50:51], 0, v[0:1]
	v_mov_b32_e32 v0, v48
	v_mov_b32_e32 v1, v48
	v_mov_b32_e32 v2, v48
	v_mov_b32_e32 v3, v48
	v_mov_b32_e32 v4, v48
	v_mov_b32_e32 v5, v48
	v_mov_b32_e32 v6, v48
	v_mov_b32_e32 v7, v48
	v_mov_b32_e32 v9, v48
	v_mov_b32_e32 v10, v48
	v_mov_b32_e32 v12, v48
	v_mov_b32_e32 v14, v48
	v_mov_b32_e32 v46, v48
	v_mov_b32_e32 v47, v48
	v_mov_b32_e32 v16, v48
	v_mov_b32_e32 v17, v48
	v_mov_b32_e32 v18, v48
	v_mov_b32_e32 v19, v48
	v_mov_b32_e32 v20, v48
	v_mov_b32_e32 v21, v48
	v_mov_b32_e32 v22, v48
	v_mov_b32_e32 v23, v48
	v_mov_b32_e32 v24, v48
	v_mov_b32_e32 v25, v48
	v_mov_b32_e32 v26, v48
	v_mov_b32_e32 v27, v48
	v_mov_b32_e32 v28, v48
	v_mov_b32_e32 v29, v48
	v_mov_b32_e32 v30, v48
	v_mov_b32_e32 v31, v48
	s_mov_b64 s[14:15], 0x6fb4080
	s_mov_b64 s[16:17], 0x6fd4080

.LBB0_1220:
	s_ashr_i32 s0, s6, 31
	s_lshr_b32 s0, s0, 26
	s_add_i32 s0, s6, s0
	s_and_b32 s1, s0, 0xffffffc0
	s_sub_i32 s5, s6, s1
	s_mul_i32 s4, s5, 0xc0
	s_lshl_b32 s2, s0, 2
	v_mov_b32_e32 v100, v155
	s_add_i32 s0, s4, 0xbf
	v_mov_b32_e32 v0, s0
	v_mov_b32_e32 v1, s4
	v_cmp_gt_i32_e32 vcc, s31, v100
	s_movk_i32 s0, 0x1800
	s_nop 0
	v_cndmask_b32_e32 v1, v0, v1, vcc
	v_add_u32_e32 v0, 0xfffff000, v1
	v_lshrrev_b32_e32 v2, 10, v0
	v_mad_u32_u24 v2, v2, s0, s0
	s_movk_i32 s0, 0xfff
	v_mov_b32_e32 v0, s2
	v_cmp_lt_i32_e32 vcc, s0, v1
	v_bfi_b32 v0, s39, v100, v0
	v_ashrrev_i32_e32 v1, 31, v0
	v_cndmask_b32_e32 v128, 0, v2, vcc
	v_lshl_add_u64 v[2:3], v[128:129], 2, s[50:51]
	v_lshl_add_u64 v[2:3], v[0:1], 2, v[2:3]
	s_barrier
	v_lshrrev_b32_e32 v244, 4, v100
	v_xor_b32_e32 v244, v244, v100
	v_and_b32_e32 v244, 7, v244
	v_lshlrev_b32_e32 v244, 4, v244
	v_mov_b32_e32 v245, 0
	v_lshrrev_b32_e32 v243, 3, v100
	v_lshlrev_b32_e32 v246, 4, v100
	s_nop 0
	v_readfirstlane_b32 s3, v246
	v_add_u32_e32 v246, s4, v243
	v_mov_b32_e32 v247, 0
	v_lshlrev_b64 v[246:247], 11, v[246:247]
	v_lshl_add_u64 v[246:247], s[46:47], 0, v[246:247]
	v_lshl_add_u64 v[246:247], v[246:247], 0, v[244:245]
	s_and_b32 s0, s2, 0xffffff00
	v_add_u32_e32 v243, s0, v243
	s_mov_b64 s[0:1], 0x20000
	s_mov_b32 m0, s3
	s_nop 0
	global_load_lds_dwordx4 v[246:247], off
	s_add_i32 m0, s3, 0x2000
	v_lshl_add_u64 v[246:247], v[246:247], 0, s[0:1]
	global_load_lds_dwordx4 v[246:247], off
	s_add_i32 m0, s3, 0x4000
	v_lshl_add_u64 v[246:247], v[246:247], 0, s[0:1]
	global_load_lds_dwordx4 v[246:247], off
	v_mov_b32_e32 v246, v243
	v_mov_b32_e32 v247, 0
	v_lshlrev_b64 v[246:247], 11, v[246:247]
	v_lshl_add_u64 v[246:247], s[56:57], 0, v[246:247]
	v_lshl_add_u64 v[246:247], v[246:247], 0, v[244:245]
	s_add_i32 m0, s3, 0x6000
	s_nop 0
	global_load_lds_dwordx4 v[246:247], off
	s_add_i32 m0, s3, 0x8000
	v_lshl_add_u64 v[246:247], v[246:247], 0, s[0:1]
	global_load_lds_dwordx4 v[246:247], off
	s_add_i32 m0, s3, 0xa000
	v_lshl_add_u64 v[246:247], v[246:247], 0, s[0:1]
	global_load_lds_dwordx4 v[246:247], off
	s_add_i32 m0, s3, 0xc000
	v_lshl_add_u64 v[246:247], v[246:247], 0, s[0:1]
	global_load_lds_dwordx4 v[246:247], off
	global_load_dword v3, v[2:3], off
	v_readlane_b32 s8, v241, 20
	v_readlane_b32 s9, v241, 21
	v_mov_b32_e32 v32, 0
	s_andn2_b64 vcc, exec, s[8:9]
	v_cndmask_b32_e64 v2, 0, 1, s[8:9]
	v_cmp_ne_u32_e64 s[0:1], 1, v2
	v_lshl_add_u32 v2, v100, 2, v167
	s_waitcnt vmcnt(0)
	ds_write_b32 v2, v3
	v_mov_b32_e32 v3, 0
	s_cbranch_vccnz .LBB0_1222
	v_lshl_add_u64 v[4:5], v[128:129], 2, s[54:55]
	v_lshlrev_b64 v[0:1], 2, v[0:1]
	v_lshl_add_u64 v[4:5], v[4:5], 0, v[0:1]
	v_lshl_add_u64 v[0:1], s[52:53], 0, v[0:1]
	global_load_dword v3, v[4:5], off
	s_nop 0
	global_load_dword v0, v[0:1], off
	s_waitcnt vmcnt(1)
	v_add_f32_e32 v1, 1.0, v3
	s_waitcnt vmcnt(0)
	v_mul_f32_e32 v3, v0, v1
.LBB0_1222:
	v_ashrrev_i32_e32 v103, 6, v100
	v_lshrrev_b32_e32 v0, 30, v103
	v_add_u32_e32 v0, v103, v0
	v_ashrrev_i32_e32 v10, 2, v0
	v_mul_i32_i24_e32 v0, 4, v10
	v_ashrrev_i32_e32 v6, 3, v100
	v_sub_u32_e32 v11, v103, v0
	v_lshrrev_b32_e32 v13, 4, v100
	v_add_u32_e32 v0, s4, v6
	v_xor_b32_e32 v7, v13, v100
	v_ashrrev_i32_e32 v1, 31, v0
	v_lshlrev_b64 v[0:1], 11, v[0:1]
	v_lshlrev_b32_e32 v7, 4, v7
	v_lshlrev_b32_e32 v109, 4, v100
	s_and_b32 s8, s2, 0xffffff00
	v_lshl_add_u64 v[4:5], s[46:47], 0, v[0:1]
	v_and_b32_e32 v128, 0x70, v7
	v_readfirstlane_b32 s2, v109
	v_add_u32_e32 v14, 0x2000, v109
	v_lshl_add_u64 v[4:5], v[4:5], 0, v[128:129]
	s_mov_b32 m0, s2
	s_mov_b64 s[10:11], 0x20000
	v_readfirstlane_b32 s2, v14
	ds_write_b32 v2, v3 offset:2048
	v_lshl_add_u64 v[2:3], v[4:5], 0, s[10:11]
	s_mov_b32 m0, s2
	s_mov_b64 s[12:13], 0x40000
	v_lshl_add_u64 v[2:3], v[4:5], 0, s[12:13]
	v_add_u32_e32 v4, 0x4000, v109
	v_add_u32_e32 v6, s8, v6
	v_readfirstlane_b32 s2, v4
	v_ashrrev_i32_e32 v7, 31, v6
	s_mov_b32 m0, s2
	v_lshlrev_b64 v[6:7], 11, v[6:7]
	v_add_u32_e32 v2, 0x6000, v109
	v_lshl_add_u64 v[8:9], s[56:57], 0, v[6:7]
	v_readfirstlane_b32 s2, v2
	v_add_u32_e32 v4, 0x8000, v109
	v_lshl_add_u64 v[8:9], v[8:9], 0, v[128:129]
	s_mov_b32 m0, s2
	v_readfirstlane_b32 s2, v4
	v_add_u32_e32 v4, 0xa000, v109
	v_lshl_add_u64 v[2:3], v[8:9], 0, s[10:11]
	s_mov_b32 m0, s2
	v_readfirstlane_b32 s2, v4
	v_lshl_add_u64 v[2:3], v[8:9], 0, s[12:13]
	s_mov_b32 m0, s2
	s_mov_b64 s[2:3], 0x60000
	v_add_u32_e32 v4, 0xc000, v109
	v_lshl_add_u64 v[2:3], v[8:9], 0, s[2:3]
	v_readfirstlane_b32 s2, v4
	s_mov_b32 m0, s2
	v_and_b32_e32 v102, 31, v100
	v_lshlrev_b32_e32 v105, 6, v11
	v_or_b32_e32 v3, v105, v102
	v_mul_i32_i24_e32 v106, 0x60, v10
	v_bfe_u32 v12, v100, 5, 1
	v_lshrrev_b32_e32 v104, 1, v100
	v_lshlrev_b32_e32 v112, 7, v3
	v_or_b32_e32 v3, v106, v102
	v_bfe_u32 v2, v100, 1, 3
	v_lshlrev_b32_e32 v113, 7, v3
	v_bitop3_b32 v3, v12, v104, 7 bitop3:0x78
	v_lshlrev_b32_e32 v111, 4, v3
	v_bitop3_b32 v3, v12, v2, 2 bitop3:0x36
	v_lshlrev_b32_e32 v110, 4, v3
	v_bitop3_b32 v3, v12, v2, 4 bitop3:0x36
	v_bitop3_b32 v2, v12, v2, 6 bitop3:0x36
	v_lshlrev_b32_e32 v107, 4, v2
	v_bitop3_b32 v2, v13, 7, v100 bitop3:0x48
	v_lshlrev_b32_e32 v2, 4, v2
	v_or_b32_e32 v6, v6, v2
	v_or_b32_e32 v0, v0, v2
	v_and_b32_e32 v101, 63, v100
	v_lshlrev_b32_e32 v108, 4, v3
	v_add_u32_e32 v114, 0x6000, v112
	v_lshl_add_u64 v[96:97], s[58:59], 0, v[6:7]
	v_lshl_add_u64 v[98:99], s[14:15], 0, v[0:1]
	s_mov_b32 s7, 0
	s_mov_b64 s[2:3], 0
	v_mov_b32_e32 v33, v32
	v_mov_b32_e32 v34, v32
	v_mov_b32_e32 v35, v32
	v_mov_b32_e32 v36, v32
	v_mov_b32_e32 v37, v32
	v_mov_b32_e32 v38, v32
	v_mov_b32_e32 v39, v32
	v_mov_b32_e32 v40, v32
	v_mov_b32_e32 v41, v32
	v_mov_b32_e32 v42, v32
	v_mov_b32_e32 v43, v32
	v_mov_b32_e32 v44, v32
	v_mov_b32_e32 v45, v32
	v_mov_b32_e32 v46, v32
	v_mov_b32_e32 v47, v32
	v_mov_b32_e32 v64, v32
	v_mov_b32_e32 v65, v32
	v_mov_b32_e32 v66, v32
	v_mov_b32_e32 v67, v32
	v_mov_b32_e32 v68, v32
	v_mov_b32_e32 v69, v32
	v_mov_b32_e32 v70, v32
	v_mov_b32_e32 v71, v32
	v_mov_b32_e32 v72, v32
	v_mov_b32_e32 v73, v32
	v_mov_b32_e32 v74, v32
	v_mov_b32_e32 v75, v32
	v_mov_b32_e32 v76, v32
	v_mov_b32_e32 v77, v32
	v_mov_b32_e32 v78, v32
	v_mov_b32_e32 v79, v32
	v_mov_b32_e32 v0, v32
	v_mov_b32_e32 v1, v32
	v_mov_b32_e32 v2, v32
	v_mov_b32_e32 v3, v32
	v_mov_b32_e32 v4, v32
	v_mov_b32_e32 v5, v32
	v_mov_b32_e32 v6, v32
	v_mov_b32_e32 v7, v32
	v_mov_b32_e32 v8, v32
	v_mov_b32_e32 v9, v32
	v_mov_b32_e32 v10, v32
	v_mov_b32_e32 v11, v32
	v_mov_b32_e32 v12, v32
	v_mov_b32_e32 v13, v32
	v_mov_b32_e32 v14, v32
	v_mov_b32_e32 v15, v32
	v_mov_b32_e32 v80, v32
	v_mov_b32_e32 v81, v32
	v_mov_b32_e32 v82, v32
	v_mov_b32_e32 v83, v32
	v_mov_b32_e32 v84, v32
	v_mov_b32_e32 v85, v32
	v_mov_b32_e32 v86, v32
	v_mov_b32_e32 v87, v32
	v_mov_b32_e32 v88, v32
	v_mov_b32_e32 v89, v32
	v_mov_b32_e32 v90, v32
	v_mov_b32_e32 v91, v32
	v_mov_b32_e32 v92, v32
	v_mov_b32_e32 v93, v32
	v_mov_b32_e32 v94, v32
	v_mov_b32_e32 v95, v32
	v_mov_b32_e32 v48, v32
	v_mov_b32_e32 v49, v32
	v_mov_b32_e32 v50, v32
	v_mov_b32_e32 v51, v32
	v_mov_b32_e32 v52, v32
	v_mov_b32_e32 v53, v32
	v_mov_b32_e32 v54, v32
	v_mov_b32_e32 v55, v32
	v_mov_b32_e32 v56, v32
	v_mov_b32_e32 v57, v32
	v_mov_b32_e32 v58, v32
	v_mov_b32_e32 v59, v32
	v_mov_b32_e32 v60, v32
	v_mov_b32_e32 v61, v32
	v_mov_b32_e32 v62, v32
	v_mov_b32_e32 v63, v32
	v_mov_b32_e32 v16, v32
	v_mov_b32_e32 v17, v32
	v_mov_b32_e32 v18, v32
	v_mov_b32_e32 v19, v32
	v_mov_b32_e32 v20, v32
	v_mov_b32_e32 v21, v32
	v_mov_b32_e32 v22, v32
	v_mov_b32_e32 v23, v32
	v_mov_b32_e32 v24, v32
	v_mov_b32_e32 v25, v32
	v_mov_b32_e32 v26, v32
	v_mov_b32_e32 v27, v32
	v_mov_b32_e32 v28, v32
	v_mov_b32_e32 v29, v32
	v_mov_b32_e32 v30, v32
	v_mov_b32_e32 v31, v32
	s_mov_b64 s[12:13], 0x8794080
	s_mov_b64 s[16:17], 0x87b4080
	s_mov_b64 s[18:19], 0x87d4080

.LBB0_1431:
	s_ashr_i32 s0, s6, 31
	s_lshr_b32 s0, s0, 26
	s_add_i32 s0, s6, s0
	s_and_b32 s1, s0, 0xffffffc0
	s_sub_i32 s5, s6, s1
	s_mul_i32 s4, s5, 0xc0
	s_lshl_b32 s2, s0, 2
	v_mov_b32_e32 v100, v155
	s_add_i32 s0, s4, 0xbf
	v_mov_b32_e32 v0, s0
	v_mov_b32_e32 v1, s4
	v_cmp_gt_i32_e32 vcc, s31, v100
	s_movk_i32 s0, 0x1800
	s_nop 0
	v_cndmask_b32_e32 v1, v0, v1, vcc
	v_add_u32_e32 v0, 0xfffff000, v1
	v_lshrrev_b32_e32 v2, 10, v0
	v_mad_u32_u24 v2, v2, s0, s0
	s_movk_i32 s0, 0xfff
	v_mov_b32_e32 v0, s2
	v_cmp_lt_i32_e32 vcc, s0, v1
	v_bfi_b32 v0, s39, v100, v0
	v_ashrrev_i32_e32 v1, 31, v0
	v_cndmask_b32_e32 v128, 0, v2, vcc
	v_lshl_add_u64 v[2:3], v[128:129], 2, s[56:57]
	v_lshl_add_u64 v[2:3], v[0:1], 2, v[2:3]
	s_barrier
	v_lshrrev_b32_e32 v244, 4, v100
	v_xor_b32_e32 v244, v244, v100
	v_and_b32_e32 v244, 7, v244
	v_lshlrev_b32_e32 v244, 4, v244
	v_mov_b32_e32 v245, 0
	v_lshrrev_b32_e32 v243, 3, v100
	v_lshlrev_b32_e32 v246, 4, v100
	s_nop 0
	v_readfirstlane_b32 s3, v246
	v_add_u32_e32 v246, s4, v243
	v_mov_b32_e32 v247, 0
	v_lshlrev_b64 v[246:247], 13, v[246:247]
	v_lshl_add_u64 v[246:247], s[52:53], 0, v[246:247]
	v_lshl_add_u64 v[246:247], v[246:247], 0, v[244:245]
	s_and_b32 s0, s2, 0xffffff00
	v_add_u32_e32 v243, s0, v243
	s_mov_b64 s[0:1], 0x80000
	s_mov_b32 m0, s3
	s_nop 0
	global_load_lds_dwordx4 v[246:247], off
	s_add_i32 m0, s3, 0x2000
	v_lshl_add_u64 v[246:247], v[246:247], 0, s[0:1]
	global_load_lds_dwordx4 v[246:247], off
	s_add_i32 m0, s3, 0x4000
	v_lshl_add_u64 v[246:247], v[246:247], 0, s[0:1]
	global_load_lds_dwordx4 v[246:247], off
	v_mov_b32_e32 v246, v243
	v_mov_b32_e32 v247, 0
	v_lshlrev_b64 v[246:247], 13, v[246:247]
	v_lshl_add_u64 v[246:247], s[48:49], 0, v[246:247]
	v_lshl_add_u64 v[246:247], v[246:247], 0, v[244:245]
	s_add_i32 m0, s3, 0x6000
	s_nop 0
	global_load_lds_dwordx4 v[246:247], off
	s_add_i32 m0, s3, 0x8000
	v_lshl_add_u64 v[246:247], v[246:247], 0, s[0:1]
	global_load_lds_dwordx4 v[246:247], off
	s_add_i32 m0, s3, 0xa000
	v_lshl_add_u64 v[246:247], v[246:247], 0, s[0:1]
	global_load_lds_dwordx4 v[246:247], off
	s_add_i32 m0, s3, 0xc000
	v_lshl_add_u64 v[246:247], v[246:247], 0, s[0:1]
	global_load_lds_dwordx4 v[246:247], off
	global_load_dword v3, v[2:3], off
	v_cndmask_b32_e64 v2, 0, 1, s[58:59]
	v_cmp_ne_u32_e64 s[0:1], 1, v2
	v_lshl_add_u32 v2, v100, 2, v167
	v_mov_b32_e32 v32, 0
	s_andn2_b64 vcc, exec, s[58:59]
	s_waitcnt vmcnt(0)
	ds_write_b32 v2, v3
	v_mov_b32_e32 v3, 0
	s_cbranch_vccnz .LBB0_1433
	v_lshl_add_u64 v[4:5], v[128:129], 2, s[46:47]
	v_lshlrev_b64 v[0:1], 2, v[0:1]
	v_lshl_add_u64 v[4:5], v[4:5], 0, v[0:1]
	v_lshl_add_u64 v[0:1], s[44:45], 0, v[0:1]
	global_load_dword v3, v[4:5], off
	s_nop 0
	global_load_dword v0, v[0:1], off
	s_waitcnt vmcnt(1)
	v_add_f32_e32 v1, 1.0, v3
	s_waitcnt vmcnt(0)
	v_mul_f32_e32 v3, v0, v1
.LBB0_1433:
	v_ashrrev_i32_e32 v103, 6, v100
	v_lshrrev_b32_e32 v0, 30, v103
	v_add_u32_e32 v0, v103, v0
	v_ashrrev_i32_e32 v10, 2, v0
	v_mul_i32_i24_e32 v0, 4, v10
	v_ashrrev_i32_e32 v6, 3, v100
	v_sub_u32_e32 v11, v103, v0
	v_lshrrev_b32_e32 v13, 4, v100
	v_add_u32_e32 v0, s4, v6
	v_xor_b32_e32 v7, v13, v100
	v_ashrrev_i32_e32 v1, 31, v0
	v_lshlrev_b64 v[0:1], 13, v[0:1]
	v_lshlrev_b32_e32 v7, 4, v7
	v_lshlrev_b32_e32 v109, 4, v100
	s_and_b32 s8, s2, 0xffffff00
	v_lshl_add_u64 v[4:5], s[52:53], 0, v[0:1]
	v_and_b32_e32 v128, 0x70, v7
	v_readfirstlane_b32 s2, v109
	v_add_u32_e32 v14, 0x2000, v109
	v_lshl_add_u64 v[4:5], v[4:5], 0, v[128:129]
	s_mov_b32 m0, s2
	v_readfirstlane_b32 s2, v14
	ds_write_b32 v2, v3 offset:2048
	v_lshl_add_u64 v[2:3], v[4:5], 0, s[16:17]
	s_mov_b32 m0, s2
	v_add_u32_e32 v6, s8, v6
	v_lshl_add_u64 v[2:3], v[4:5], 0, s[20:21]
	v_add_u32_e32 v4, 0x4000, v109
	v_ashrrev_i32_e32 v7, 31, v6
	v_readfirstlane_b32 s2, v4
	s_mov_b32 m0, s2
	v_lshlrev_b64 v[6:7], 13, v[6:7]
	v_add_u32_e32 v2, 0x6000, v109
	v_lshl_add_u64 v[8:9], s[48:49], 0, v[6:7]
	v_readfirstlane_b32 s2, v2
	v_add_u32_e32 v4, 0x8000, v109
	v_lshl_add_u64 v[8:9], v[8:9], 0, v[128:129]
	s_mov_b32 m0, s2
	v_readfirstlane_b32 s2, v4
	v_add_u32_e32 v4, 0xa000, v109
	v_lshl_add_u64 v[2:3], v[8:9], 0, s[16:17]
	s_mov_b32 m0, s2
	v_readfirstlane_b32 s2, v4
	v_lshl_add_u64 v[2:3], v[8:9], 0, s[20:21]
	s_mov_b32 m0, s2
	s_mov_b64 s[2:3], 0x180000
	v_add_u32_e32 v4, 0xc000, v109
	v_lshl_add_u64 v[2:3], v[8:9], 0, s[2:3]
	v_readfirstlane_b32 s2, v4
	s_mov_b32 m0, s2
	v_and_b32_e32 v102, 31, v100
	v_lshlrev_b32_e32 v105, 6, v11
	v_or_b32_e32 v3, v105, v102
	v_mul_i32_i24_e32 v106, 0x60, v10
	v_bfe_u32 v12, v100, 5, 1
	v_lshrrev_b32_e32 v104, 1, v100
	v_lshlrev_b32_e32 v112, 7, v3
	v_or_b32_e32 v3, v106, v102
	v_bfe_u32 v2, v100, 1, 3
	v_lshlrev_b32_e32 v113, 7, v3
	v_bitop3_b32 v3, v12, v104, 7 bitop3:0x78
	v_lshlrev_b32_e32 v111, 4, v3
	v_bitop3_b32 v3, v12, v2, 2 bitop3:0x36
	v_lshlrev_b32_e32 v110, 4, v3
	v_bitop3_b32 v3, v12, v2, 4 bitop3:0x36
	v_bitop3_b32 v2, v12, v2, 6 bitop3:0x36
	v_lshlrev_b32_e32 v107, 4, v2
	v_bitop3_b32 v2, v13, 7, v100 bitop3:0x48
	v_lshlrev_b32_e32 v2, 4, v2
	v_or_b32_e32 v6, v6, v2
	v_or_b32_e32 v0, v0, v2
	v_and_b32_e32 v101, 63, v100
	v_lshlrev_b32_e32 v108, 4, v3
	v_add_u32_e32 v114, 0x6000, v112
	v_lshl_add_u64 v[96:97], s[60:61], 0, v[6:7]
	v_lshl_add_u64 v[98:99], s[14:15], 0, v[0:1]
	s_mov_b32 s7, 0
	s_mov_b64 s[2:3], 0
	v_mov_b32_e32 v33, v32
	v_mov_b32_e32 v34, v32
	v_mov_b32_e32 v35, v32
	v_mov_b32_e32 v36, v32
	v_mov_b32_e32 v37, v32
	v_mov_b32_e32 v38, v32
	v_mov_b32_e32 v39, v32
	v_mov_b32_e32 v40, v32
	v_mov_b32_e32 v41, v32
	v_mov_b32_e32 v42, v32
	v_mov_b32_e32 v43, v32
	v_mov_b32_e32 v44, v32
	v_mov_b32_e32 v45, v32
	v_mov_b32_e32 v46, v32
	v_mov_b32_e32 v47, v32
	v_mov_b32_e32 v64, v32
	v_mov_b32_e32 v65, v32
	v_mov_b32_e32 v66, v32
	v_mov_b32_e32 v67, v32
	v_mov_b32_e32 v68, v32
	v_mov_b32_e32 v69, v32
	v_mov_b32_e32 v70, v32
	v_mov_b32_e32 v71, v32
	v_mov_b32_e32 v72, v32
	v_mov_b32_e32 v73, v32
	v_mov_b32_e32 v74, v32
	v_mov_b32_e32 v75, v32
	v_mov_b32_e32 v76, v32
	v_mov_b32_e32 v77, v32
	v_mov_b32_e32 v78, v32
	v_mov_b32_e32 v79, v32
	v_mov_b32_e32 v0, v32
	v_mov_b32_e32 v1, v32
	v_mov_b32_e32 v2, v32
	v_mov_b32_e32 v3, v32
	v_mov_b32_e32 v4, v32
	v_mov_b32_e32 v5, v32
	v_mov_b32_e32 v6, v32
	v_mov_b32_e32 v7, v32
	v_mov_b32_e32 v8, v32
	v_mov_b32_e32 v9, v32
	v_mov_b32_e32 v10, v32
	v_mov_b32_e32 v11, v32
	v_mov_b32_e32 v12, v32
	v_mov_b32_e32 v13, v32
	v_mov_b32_e32 v14, v32
	v_mov_b32_e32 v15, v32
	v_mov_b32_e32 v80, v32
	v_mov_b32_e32 v81, v32
	v_mov_b32_e32 v82, v32
	v_mov_b32_e32 v83, v32
	v_mov_b32_e32 v84, v32
	v_mov_b32_e32 v85, v32
	v_mov_b32_e32 v86, v32
	v_mov_b32_e32 v87, v32
	v_mov_b32_e32 v88, v32
	v_mov_b32_e32 v89, v32
	v_mov_b32_e32 v90, v32
	v_mov_b32_e32 v91, v32
	v_mov_b32_e32 v92, v32
	v_mov_b32_e32 v93, v32
	v_mov_b32_e32 v94, v32
	v_mov_b32_e32 v95, v32
	v_mov_b32_e32 v48, v32
	v_mov_b32_e32 v49, v32
	v_mov_b32_e32 v50, v32
	v_mov_b32_e32 v51, v32
	v_mov_b32_e32 v52, v32
	v_mov_b32_e32 v53, v32
	v_mov_b32_e32 v54, v32
	v_mov_b32_e32 v55, v32
	v_mov_b32_e32 v56, v32
	v_mov_b32_e32 v57, v32
	v_mov_b32_e32 v58, v32
	v_mov_b32_e32 v59, v32
	v_mov_b32_e32 v60, v32
	v_mov_b32_e32 v61, v32
	v_mov_b32_e32 v62, v32
	v_mov_b32_e32 v63, v32
	v_mov_b32_e32 v16, v32
	v_mov_b32_e32 v17, v32
	v_mov_b32_e32 v18, v32
	v_mov_b32_e32 v19, v32
	v_mov_b32_e32 v20, v32
	v_mov_b32_e32 v21, v32
	v_mov_b32_e32 v22, v32
	v_mov_b32_e32 v23, v32
	v_mov_b32_e32 v24, v32
	v_mov_b32_e32 v25, v32
	v_mov_b32_e32 v26, v32
	v_mov_b32_e32 v27, v32
	v_mov_b32_e32 v28, v32
	v_mov_b32_e32 v29, v32
	v_mov_b32_e32 v30, v32
	v_mov_b32_e32 v31, v32
